# P2 epilogue: non-gate tiles skip the bias loads and their full vmcnt(0) drain (bias registers zeroed instead), on top of v4
# speedup vs baseline: 1.0079x; 1.0079x over previous
;     __device__ __forceinline__ void operator()(const f32x4 (&acc)[2][2][4][2], const UnitD& u, int wr, int wc, int lane, LAS unsigned char* eb) const {
;     ...
;         const int fr = lane & 15, fq = lane >> 4;
;         const int pn = u.pn; const bool plain = (u.tag != 0);
;         bf16_t* Ob = plain ? O1 : O; const int ld = plain ? ldc1 : ldc;
;         int mode = 0;
;         if (!plain && pn >= 48) mode = 2;
;         const int colw = pn * BM + wc * 64;
;         const int bofs = (mode == 2) ? (colw - C_GATE) : 0; const float bsc = (mode == 2) ? -LOG2E : 0.f;
;         f32x4 bv[2][2];
; #pragma unroll
;         for (int bj = 0; bj < 2; ++bj)
; #pragma unroll
;             for (int n = 0; n < 2; ++n) bv[bj][n] = *(const f32x4*)(bias + bofs + 32 * bj + 8 * fq + 4 * n) * bsc;
.LBB0_225:
	s_cmp_eq_u32 s58, 0
	s_cselect_b64 s[30:31], -1, 0
	s_cmp_gt_i32 s2, 47
	s_cselect_b64 s[34:35], -1, 0
	s_lshl_b32 s2, s2, 8
	s_or_b32 s28, s2, s52
	s_add_i32 s21, s28, 0xffffd000
	s_and_b64 s[2:3], s[30:31], s[34:35]
	s_ashr_i32 s23, s21, 31
	s_and_b64 vcc, s[2:3], exec
	v_mov_b32_e32 v168, v162
	s_cselect_b32 s35, s23, 0
	s_cselect_b32 s34, s21, 0
	v_mov_b32_e32 v128, 0xbfb8aa3b
	v_ashrrev_i32_e32 v160, 4, v168
	s_lshl_b64 s[34:35], s[34:35], 2
	v_cndmask_b32_e64 v156, 0, v128, s[2:3]
	s_add_u32 s34, s46, s34
	v_lshlrev_b32_e32 v128, 3, v160
	s_addc_u32 s35, s47, s35
	v_ashrrev_i32_e32 v129, 31, v128
	v_lshl_add_u64 v[132:133], v[128:129], 2, s[34:35]
	s_cbranch_vccz .Lp2_nobias
	global_load_dwordx4 v[140:143], v[132:133], off
	global_load_dwordx4 v[136:139], v[132:133], off offset:16
	global_load_dwordx4 v[128:131], v[132:133], off offset:144
	s_nop 0
	global_load_dwordx4 v[132:135], v[132:133], off offset:128
	s_waitcnt vmcnt(0)
	s_branch .Lp2_bias_done
.Lp2_nobias:
	v_mov_b32_e32 v128, 0
	v_mov_b32_e32 v129, 0
	v_mov_b32_e32 v130, 0
	v_mov_b32_e32 v131, 0
	v_mov_b32_e32 v132, 0
	v_mov_b32_e32 v133, 0
	v_mov_b32_e32 v134, 0
	v_mov_b32_e32 v135, 0
	v_mov_b32_e32 v136, 0
	v_mov_b32_e32 v137, 0
	v_mov_b32_e32 v138, 0
	v_mov_b32_e32 v139, 0
	v_mov_b32_e32 v140, 0
	v_mov_b32_e32 v141, 0
	v_mov_b32_e32 v142, 0
	v_mov_b32_e32 v143, 0
.Lp2_bias_done:
	s_mov_b64 s[34:35], -1
	v_pk_fma_f32 v[126:127], v[156:157], v[142:143], v[126:127] op_sel_hi:[0,1,1]
	v_pk_fma_f32 v[124:125], v[156:157], v[140:141], v[124:125] op_sel_hi:[0,1,1]
	v_pk_fma_f32 v[122:123], v[156:157], v[138:139], v[122:123] op_sel_hi:[0,1,1]
	v_pk_fma_f32 v[120:121], v[156:157], v[136:137], v[120:121] op_sel_hi:[0,1,1]
	s_cbranch_vccnz .LBB0_227
	s_mov_b64 s[34:35], 0
